# every s_setprio deleted, no static raise (separates the cost of the flips from the raise)
# baseline (speedup 1.0000x reference)
; DI int half_() { return __builtin_amdgcn_readfirstlane((int)(threadIdx.x >> 8)); }
; DI void grid_barrier(unsigned* bar, unsigned gen) {
;     ...
;   if (threadIdx.x == 0) {
;     __builtin_amdgcn_fence(__ATOMIC_RELEASE, "agent");
;     const unsigned grp = blockIdx.x & 15u;
;     const unsigned nblk = (gridDim.x + 15u - grp) >> 4;
; __global__ void __launch_bounds__(512, 2) mega(Params p_unused, int ph0, int ph1) {
;   __shared__ __attribute__((aligned(16))) unsigned char lds_all[LDS_BYTES];
;   unsigned char* ldsb = lds_all + half_() * LDS_HALF;
;   cg::grid_group grid = cg::this_grid();
;   for (int ph = ph0; ph < ph1; ++ph) {
;     const __attribute__((address_space(4))) Params* pp = (const __attribute__((address_space(4))) Params*)__builtin_amdgcn_kernarg_segment_ptr();
;     asm volatile("" : "+s"(pp));
;     PREF p = *pp;
;     if (ph1 < 0) grid.sync();
;     if (ph > ph0) grid_barrier(p.bar, (unsigned)(ph - ph0));
;     if (ph == 0) { run_phase<9>(p, 0, ldsb, lds_all); continue; }
;     int l = (ph - 1) / NPH_LAYER; const int j = (ph - 1) % NPH_LAYER;
;     asm volatile("" : "+s"(l));
.LBB0_1:
	s_lshr_b32 s33, s0, 8
	v_readlane_b32 s0, v254, 1
	v_readlane_b32 s1, v254, 2
	s_add_u32 s2, s0, 0x1a8
	s_addc_u32 s3, s1, 0
	v_writelane_b32 v254, s2, 5
	v_lshrrev_b32_e32 v1, 20, v0
	v_lshrrev_b32_e32 v0, 10, v0
	v_writelane_b32 v254, s3, 6
	v_or_b32_e32 v0, v0, v1
	s_movk_i32 s2, 0x3ff
	v_and_or_b32 v0, v0, s2, v168
	v_readlane_b32 s8, v254, 3
	v_cmp_eq_u32_e64 s[2:3], 0, v0
	v_readlane_b32 s9, v254, 4
	s_load_dword s5, s[0:1], 0x1a8
	v_writelane_b32 v254, s2, 7
	s_cmp_lt_i32 s9, 0
	s_cselect_b64 s[0:1], -1, 0
	v_writelane_b32 v254, s3, 8
	v_cmp_eq_u32_e64 s[2:3], 0, v168
	s_waitcnt lgkmcnt(0)
	s_lshr_b32 s45, s5, 3
	s_mul_i32 s33, s33, 0x12400
	v_writelane_b32 v254, s2, 9
	v_cndmask_b32_e64 v0, 0, 1, s[0:1]
	v_cmp_ne_u32_e64 s[0:1], 1, v0
	v_writelane_b32 v254, s3, 10
	v_mbcnt_lo_u32_b32 v0, -1, 0
	v_readlane_b32 s4, v254, 0
	s_and_b32 s2, s4, 15
	s_xor_b32 s3, s2, 15
	s_add_i32 s3, s5, s3
	s_lshr_b32 s3, s3, 4
	s_lshl_b32 s2, s2, 6
	s_lshr_b32 s46, s4, 3
	s_cmpk_lt_u32 s4, 0x200
	v_writelane_b32 v254, s3, 11
	s_cselect_b64 s[6:7], -1, 0
	s_lshl_b32 s3, s4, 4
	s_and_b32 s47, s3, 0x70
	s_lshl_b32 s3, s4, 3
	s_lshl_b32 s48, s5, 3
	v_writelane_b32 v254, s6, 12
	s_cmpk_lt_i32 s4, 0x100
	s_mov_b32 s53, 0
	v_writelane_b32 v254, s7, 13
	s_cselect_b64 s[6:7], -1, 0
	v_writelane_b32 v254, s6, 14
	s_ashr_i32 s49, s48, 31
	s_lshl_b32 s64, s5, 9
	v_writelane_b32 v254, s7, 15
	s_add_i32 s6, s33, 0x12000
	v_writelane_b32 v254, s6, 16
	s_lshl_b32 s6, s4, 9
	v_writelane_b32 v254, s6, 17
	s_lshl_b64 s[6:7], s[48:49], 11
	v_writelane_b32 v254, s6, 18
	s_ashr_i32 s65, s64, 31
	s_lshl_b32 s70, s4, 1
	v_writelane_b32 v254, s7, 19
	v_writelane_b32 v254, s3, 20
	s_addk_i32 s3, 0x4000
	v_writelane_b32 v254, s3, 21
	s_lshl_b32 s3, s4, 8
	v_writelane_b32 v254, s3, 22
	s_lshl_b32 s3, s5, 8
	v_writelane_b32 v254, s3, 23
	s_add_i32 s3, s33, 0x4000
	v_writelane_b32 v254, s3, 24
	s_lshl_b32 s3, s4, 6
	v_writelane_b32 v254, s3, 25
	s_lshl_b64 s[6:7], s[64:65], 4
	v_writelane_b32 v254, s6, 26
	s_lshl_b32 s3, s5, 10
	s_lshl_b32 s71, s5, 1
	v_writelane_b32 v254, s7, 27
	s_lshl_b64 s[6:7], s[64:65], 5
	v_writelane_b32 v254, s6, 28
	s_lshl_b32 s81, s4, 7
	s_lshl_b32 s84, s5, 7
	v_writelane_b32 v254, s7, 29
	s_lshl_b64 s[6:7], s[48:49], 12
	v_writelane_b32 v254, s6, 30
	s_lshl_b32 s85, s5, 6
	s_movk_i32 s66, 0x200
	v_writelane_b32 v254, s7, 31
	v_writelane_b32 v254, s5, 32
	v_writelane_b32 v254, s3, 33
	s_lshl_b64 s[4:5], s[64:65], 2
	v_writelane_b32 v254, s4, 34
	v_and_b32_e32 v169, 0xff, v168
	s_movk_i32 s67, 0x100
	v_writelane_b32 v254, s5, 35
	v_writelane_b32 v254, s0, 36
	s_lshl_b64 s[72:73], s[64:65], 6
	v_mov_b32_e32 v1, 0
	v_writelane_b32 v254, s1, 37
	s_lshl_b32 s0, s2, 2
	v_writelane_b32 v254, s0, 38
	v_writelane_b32 v254, s45, 39
	v_writelane_b32 v254, s46, 40
	v_writelane_b32 v254, s47, 41
	s_mov_b32 s0, s48
	v_writelane_b32 v254, s0, 42
	s_mov_b32 s88, 0x10000
	v_mov_b32_e32 v170, 0x1000
	v_writelane_b32 v254, s1, 43
	s_mov_b32 s0, s64
	s_mov_b64 s[76:77], 0x80
	s_mov_b64 s[78:79], 0x40080
	s_mov_b64 s[42:43], 0x12b0100
	s_mov_b64 s[82:83], 0x100
	s_mov_b64 s[86:87], 0x40100
	s_mov_b64 s[90:91], 0x180
	s_movk_i32 s89, 0x180
	s_movk_i32 s92, 0x210
	s_movk_i32 s93, 0x80
	v_mov_b32_e32 v171, 0x3727c5ac
	s_mov_b32 s61, 0x800000
	s_movk_i32 s80, 0x1000
	s_mov_b64 s[50:51], 0x580100
	s_mov_b64 s[38:39], 0x980100
	s_mov_b64 s[4:5], 0x580180
	s_mov_b64 s[74:75], 0x980180
	s_movk_i32 s60, 0x1540
	s_movk_i32 s96, 0x300
	s_movk_i32 s97, 0x90
	s_mov_b32 s94, 0xff800000
	v_mbcnt_hi_u32_b32 v172, -1, v0
	v_mov_b32_e32 v163, 1.0
	s_mov_b64 s[2:3], 0xaa000
	v_mov_b32_e32 v173, 0x358637bd
	s_movk_i32 s95, 0x400
	s_mov_b64 s[6:7], 0x40180
	s_movk_i32 s58, 0xaa0
	s_movk_i32 s59, 0x600
	s_movk_i32 s54, 0x2a80
	v_mov_b32_e32 v174, 0x3c0881c4
	v_mov_b32_e32 v175, 0xbab64f3b
	v_mov_b32_e32 v176, 0xff800000
	v_mov_b32_e32 v177, 0x7f800000
	v_not_b32_e32 v178, 63
	v_not_b32_e32 v179, 31
	v_mov_b32_e32 v180, 0x7fc00000
	v_mov_b32_e32 v181, 0x37000000
	s_mov_b32 s34, s8
	v_writelane_b32 v254, s0, 44
	s_nop 1
	v_writelane_b32 v254, s1, 45
	v_readfirstlane_b32 s0, v168
	s_lshr_b32 s0, s0, 8
	s_cmp_eq_u32 s0, 0
	s_cbranch_scc1 .Lmy_prio_done
